# v31: latent attention K / V^T LDS row stride 272 -> 288 bytes (removes the 2-way bank conflict of every ds_read_b128 lane group) in staging, loop and peeled last tile
# speedup vs baseline: 1.0053x; 1.0053x over previous
.LBB0_747:
	s_and_b64 vcc, exec, s[10:11]
	s_cbranch_vccz .LBB0_751
	v_mov_b32_e32 v10, v232
	s_load_dwordx8 s[52:59], s[44:45], 0x60
	v_and_b32_e32 v181, 63, v10
	v_readlane_b32 s10, v255, 20
	v_mov_b32_e32 v3, v0
	s_load_dwordx2 s[42:43], s[44:45], 0xb0
	v_or_b32_e32 v2, s10, v181
	v_lshlrev_b64 v[2:3], 2, v[2:3]
	s_waitcnt lgkmcnt(0)
	v_lshl_add_u64 v[4:5], s[52:53], 0, v[2:3]
	global_load_dword v11, v[4:5], off
	v_lshl_add_u64 v[4:5], s[54:55], 0, v[2:3]
	global_load_dword v12, v[4:5], off
	v_lshl_add_u64 v[4:5], s[56:57], 0, v[2:3]
	v_lshl_add_u64 v[2:3], s[58:59], 0, v[2:3]
	global_load_dword v13, v[4:5], off
	global_load_dword v14, v[2:3], off
	s_add_i32 s6, s37, s48
	s_lshl_b32 s14, s36, 7
	s_lshl_b32 s30, s36, 8
	v_readlane_b32 s11, v255, 21
	s_add_u32 s10, s42, s47
	s_addc_u32 s11, s43, s46
	s_add_u32 s36, s10, s30
	s_addc_u32 s37, s11, 0
	s_lshl_b32 s10, s27, 10
	s_or_b32 s10, s14, s10
	s_mul_hi_i32 s11, s10, 0x2200
	s_mulk_i32 s10, 0x2200
	v_ashrrev_i32_e32 v50, 4, v10
	s_add_u32 s10, s42, s10
	v_ashrrev_i32_e32 v51, 31, v50
	v_and_b32_e32 v177, 15, v10
	s_addc_u32 s11, s43, s11
	v_lshlrev_b64 v[52:53], 11, v[50:51]
	s_add_u32 s40, s10, 0xe010000
	v_lshl_add_u64 v[2:3], s[36:37], 0, v[52:53]
	v_lshlrev_b32_e32 v124, 4, v177
	v_mov_b32_e32 v125, v0
	s_addc_u32 s41, s11, 0
	v_lshl_add_u64 v[2:3], v[2:3], 0, v[124:125]
	s_mov_b32 s15, 0x16810000
	v_mov_b64_e32 v[4:5], s[40:41]
	s_movk_i32 s35, 0x2200
	v_add_co_u32_e32 v6, vcc, s15, v2
	v_mad_i64_i32 v[4:5], s[36:37], v50, s35, v[4:5]
	s_nop 0
	v_addc_co_u32_e32 v7, vcc, 0, v3, vcc
	s_mov_b32 s15, 0x16820000
	v_lshl_add_u64 v[4:5], v[4:5], 0, v[124:125]
	global_load_dwordx4 v[18:21], v[6:7], off
	global_load_dwordx4 v[22:25], v[4:5], off
	v_add_co_u32_e32 v6, vcc, s15, v2
	s_mov_b32 s15, 0x44000
	s_nop 0
	v_addc_co_u32_e32 v7, vcc, 0, v3, vcc
	v_add_co_u32_e32 v8, vcc, s15, v4
	s_mov_b32 s15, 0x16830000
	s_nop 0
	v_addc_co_u32_e32 v9, vcc, 0, v5, vcc
	global_load_dwordx4 v[26:29], v[6:7], off
	global_load_dwordx4 v[30:33], v[8:9], off
	v_add_co_u32_e32 v6, vcc, s15, v2
	s_mov_b32 s15, 0x88000
	s_nop 0
	v_addc_co_u32_e32 v7, vcc, 0, v3, vcc
	v_add_co_u32_e32 v8, vcc, s15, v4
	s_mov_b32 s15, 0x16840000
	s_nop 0
	v_addc_co_u32_e32 v9, vcc, 0, v5, vcc
	v_add_co_u32_e32 v2, vcc, s15, v2
	s_mov_b32 s15, 0xcc000
	s_nop 0
	v_addc_co_u32_e32 v3, vcc, 0, v3, vcc
	v_add_co_u32_e32 v4, vcc, s15, v4
	global_load_dwordx4 v[34:37], v[6:7], off
	global_load_dwordx4 v[38:41], v[8:9], off
	v_addc_co_u32_e32 v5, vcc, 0, v5, vcc
	global_load_dwordx4 v[42:45], v[2:3], off
	global_load_dwordx4 v[46:49], v[4:5], off
	v_ashrrev_i32_e32 v4, 2, v10
	v_and_b32_e32 v4, 0xffffffe0, v4
	v_add_u32_e32 v180, s6, v4
	v_ashrrev_i32_e32 v182, 6, v10
	v_and_b32_e32 v179, 1, v182
	v_mov_b32_e32 v55, v0
	v_lshlrev_b32_e32 v54, 7, v179
	s_waitcnt vmcnt(10)
	v_mul_f32_e32 v2, v11, v12
	ds_bpermute_b32 v2, v1, v2
	v_and_b32_e32 v56, 48, v10
	v_mov_b32_e32 v57, v0
	s_waitcnt vmcnt(8)
	v_mul_f32_e32 v3, v13, v14
	ds_bpermute_b32 v3, v1, v3
	s_waitcnt lgkmcnt(1)
	v_fmac_f32_e32 v2, v11, v12
	ds_bpermute_b32 v5, v176, v2
	s_mov_b32 s6, 0x14610000
	s_mov_b64 s[36:37], 0x14610000
	s_waitcnt lgkmcnt(1)
	v_fmac_f32_e32 v3, v13, v14
	ds_bpermute_b32 v6, v176, v3
	s_waitcnt lgkmcnt(1)
	v_add_f32_e32 v4, v2, v5
	v_or_b32_e32 v2, v180, v177
	v_bfe_u32 v178, v10, 4, 2
	v_lshlrev_b32_e32 v51, 2, v50
	s_waitcnt lgkmcnt(0)
	v_add_f32_e32 v5, v3, v6
	ds_bpermute_b32 v6, v175, v4
	ds_bpermute_b32 v7, v175, v5
	v_ashrrev_i32_e32 v3, 31, v2
	v_lshlrev_b64 v[2:3], 11, v[2:3]
	v_lshl_add_u64 v[2:3], s[42:43], 0, v[2:3]
	s_waitcnt lgkmcnt(1)
	v_add_f32_e32 v4, v4, v6
	s_waitcnt lgkmcnt(0)
	v_add_f32_e32 v5, v5, v7
	ds_bpermute_b32 v6, v174, v4
	ds_bpermute_b32 v7, v174, v5
	v_lshl_add_u64 v[2:3], v[2:3], 0, s[30:31]
	v_lshl_add_u64 v[2:3], v[2:3], 0, v[54:55]
	v_lshrrev_b32_e32 v55, 1, v50
	s_waitcnt lgkmcnt(1)
	v_add_f32_e32 v132, v4, v6
	s_waitcnt lgkmcnt(0)
	v_add_f32_e32 v133, v5, v7
	v_lshl_add_u64 v[6:7], v[2:3], 0, v[56:57]
	v_add_co_u32_e32 v4, vcc, s6, v6
	s_mov_b32 s6, 0x14618000
	s_nop 0
	v_addc_co_u32_e32 v5, vcc, 0, v7, vcc
	v_lshl_add_u64 v[2:3], v[6:7], 0, s[36:37]
	v_add_co_u32_e32 v6, vcc, s6, v6
	global_load_dwordx4 v[10:13], v[4:5], off
	s_nop 0
	global_load_dwordx4 v[2:5], v[2:3], off offset:64
	v_addc_co_u32_e32 v7, vcc, 0, v7, vcc
	global_load_dwordx4 v[14:17], v[6:7], off
	s_nop 0
	global_load_dwordx4 v[6:9], v[6:7], off offset:64
	v_and_b32_e32 v51, 16, v51
	v_and_b32_e32 v55, 12, v55
	v_and_b32_e32 v57, 0xfffffe3, v50
	v_or3_b32 v51, v57, v51, v55
	s_movk_i32 s6, 0x120
	v_mul_lo_u32 v55, v50, s6
	v_mad_u64_u32 v[126:127], s[36:37], v51, s6, v[124:125]
	s_mov_b32 s6, 0x12000
	v_add3_u32 v127, v55, v124, s6
	v_add_u32_e32 v51, 0, v126
	v_add_u32_e32 v55, 0, v127
	s_waitcnt vmcnt(11)
	ds_write_b128 v51, v[18:21]
	s_waitcnt vmcnt(10)
	ds_write_b128 v55, v[22:25]
	s_waitcnt vmcnt(9)
	ds_write_b128 v51, v[26:29] offset:9216
	s_waitcnt vmcnt(8)
	ds_write_b128 v55, v[30:33] offset:9216
	s_waitcnt vmcnt(7)
	ds_write_b128 v51, v[34:37] offset:18432
	s_waitcnt vmcnt(6)
	ds_write_b128 v55, v[38:41] offset:18432
	s_waitcnt vmcnt(5)
	ds_write_b128 v51, v[42:45] offset:27648
	s_waitcnt vmcnt(4)
	ds_write_b128 v55, v[46:49] offset:27648
	s_add_i32 s6, 0, 0x12000
	v_mul_u32_u24_e32 v19, 0x120, v177
	v_add3_u32 v183, s6, v56, v19
	s_lshl_b32 s6, s26, 3
	s_and_b32 s6, s6, 0x700
	ds_bpermute_b32 v134, v173, v132
	ds_bpermute_b32 v135, v173, v133
	s_add_u32 s6, s42, s6
	v_add_u32_e32 v18, 0, v54
	s_addc_u32 s18, s43, 0
	v_add3_u32 v137, v18, v56, v19
	s_add_u32 s26, s6, s47
	v_mov_b64_e32 v[18:19], s[10:11]
	s_addc_u32 s27, s18, s46
	v_mad_i64_i32 v[130:131], s[10:11], v50, s35, v[18:19]
	v_mov_b32_e32 v18, 0
	s_mov_b32 s15, 0
	v_lshl_add_u64 v[128:129], s[26:27], 0, v[52:53]
	v_mov_b32_e32 v19, v18
	v_mov_b32_e32 v20, v18
	v_mov_b32_e32 v21, v18
	v_mov_b32_e32 v22, v18
	v_mov_b32_e32 v23, v18
	v_mov_b32_e32 v24, v18
	v_mov_b32_e32 v25, v18
	v_mov_b32_e32 v26, v18
	v_mov_b32_e32 v27, v18
	v_mov_b32_e32 v28, v18
	v_mov_b32_e32 v29, v18
	v_mov_b32_e32 v30, v18
	v_mov_b32_e32 v31, v18
	v_mov_b32_e32 v32, v18
	v_mov_b32_e32 v33, v18
	v_mov_b32_e32 v38, v18
	v_mov_b32_e32 v39, v18
	v_mov_b32_e32 v40, v18
	v_mov_b32_e32 v41, v18
	v_mov_b32_e32 v46, v18
	v_mov_b32_e32 v47, v18
	v_mov_b32_e32 v48, v18
	v_mov_b32_e32 v49, v18
	v_mov_b32_e32 v62, v18
	v_mov_b32_e32 v63, v18
	v_mov_b32_e32 v64, v18
	v_mov_b32_e32 v65, v18
	v_mov_b32_e32 v74, v18
	v_mov_b32_e32 v75, v18
	v_mov_b32_e32 v76, v18
	v_mov_b32_e32 v77, v18
	v_mov_b32_e32 v34, v18
	v_mov_b32_e32 v35, v18
	v_mov_b32_e32 v36, v18
	v_mov_b32_e32 v37, v18
	v_mov_b32_e32 v42, v18
	v_mov_b32_e32 v43, v18
	v_mov_b32_e32 v44, v18
	v_mov_b32_e32 v45, v18
	v_mov_b32_e32 v50, v18
	v_mov_b32_e32 v51, v18
	v_mov_b32_e32 v52, v18
	v_mov_b32_e32 v53, v18
	v_mov_b32_e32 v54, v18
	v_mov_b32_e32 v55, v18
	v_mov_b32_e32 v56, v18
	v_mov_b32_e32 v57, v18
	v_mov_b32_e32 v58, v18
	v_mov_b32_e32 v59, v18
	v_mov_b32_e32 v60, v18
	v_mov_b32_e32 v61, v18
	v_mov_b32_e32 v66, v18
	v_mov_b32_e32 v67, v18
	v_mov_b32_e32 v68, v18
	v_mov_b32_e32 v69, v18
	v_mov_b32_e32 v70, v18
	v_mov_b32_e32 v71, v18
	v_mov_b32_e32 v72, v18
	v_mov_b32_e32 v73, v18
	v_mov_b32_e32 v78, v18
	v_mov_b32_e32 v79, v18
	v_mov_b32_e32 v80, v18
	v_mov_b32_e32 v81, v18
	v_mov_b32_e32 v122, v18
	v_mov_b32_e32 v123, v18
	s_mov_b32 s11, 0xe054000
	s_mov_b32 s18, 0x16870000
	s_mov_b32 s26, 0xe098000
	s_mov_b32 s27, 0x16880000
	s_mov_b32 s30, 0xe0dc000
	s_mov_b64 s[36:37], 0x40000
	s_waitcnt lgkmcnt(0)
	s_barrier
	s_waitcnt vmcnt(0) lgkmcnt(0)
	v_writelane_b32 v175, s64, 0
	v_writelane_b32 v175, s65, 1
	v_writelane_b32 v175, s66, 2
	v_writelane_b32 v175, s67, 3
	v_writelane_b32 v175, s68, 4
	v_writelane_b32 v175, s69, 5
	v_writelane_b32 v175, s70, 6
	v_writelane_b32 v175, s71, 7
	v_writelane_b32 v175, s72, 8
	v_writelane_b32 v175, s73, 9
	v_writelane_b32 v175, s74, 10
	v_writelane_b32 v175, s75, 11
	v_writelane_b32 v175, s76, 12
	v_writelane_b32 v175, s77, 13
	v_writelane_b32 v175, s78, 14
	v_writelane_b32 v175, s79, 15
	v_lshl_add_u64 v[138:139], v[128:129], 0, v[124:125]
	v_lshl_add_u64 v[140:141], v[130:131], 0, v[124:125]
	s_nop 1
	v_readfirstlane_b32 s64, v138
	v_readfirstlane_b32 s65, v139
	v_readfirstlane_b32 s72, v140
	v_readfirstlane_b32 s73, v141
	s_nop 3
	v_subrev_u32_e32 v124, s64, v138
	v_subrev_u32_e32 v125, s72, v140
	s_add_u32 s66, s64, s97
	s_addc_u32 s67, s65, 0
	s_add_u32 s68, s64, s18
	s_addc_u32 s69, s65, 0
	s_add_u32 s70, s64, s27
	s_addc_u32 s71, s65, 0
	s_add_u32 s64, s64, s96
	s_addc_u32 s65, s65, 0
	s_add_u32 s74, s72, s11
	s_addc_u32 s75, s73, 0
	s_add_u32 s74, s74, 0x100
	s_addc_u32 s75, s75, 0
	s_add_u32 s76, s72, s26
	s_addc_u32 s77, s73, 0
	s_add_u32 s76, s76, 0x100
	s_addc_u32 s77, s77, 0
	s_add_u32 s78, s72, s30
	s_addc_u32 s79, s73, 0
	s_add_u32 s78, s78, 0x100
	s_addc_u32 s79, s79, 0
	s_add_u32 s72, s72, s91
	s_addc_u32 s73, s73, 0
	s_add_u32 s72, s72, 0x100
	s_addc_u32 s73, s73, 0
	s_mov_b32 s15, 0
	s_nop 4
.Lattn_nf_loop:
	s_and_b32 s10, s15, 1
	s_mul_i32 s6, s10, 0x9000
	v_add_u32_e32 v136, s6, v137
	v_add_u32_e32 v170, s6, v183
	s_sub_u32 s10, 0x9000, s6
	ds_read_b128 v[98:101], v136 offset:0
	ds_read_b128 v[102:105], v136 offset:64
	ds_read_b128 v[106:109], v136 offset:4608
	ds_read_b128 v[110:113], v136 offset:4672
	v_add_u32_e32 v171, s10, v126
	v_add_u32_e32 v173, s10, v127
	global_load_dwordx4 v[82:85], v124, s[64:65]
	global_load_dwordx4 v[86:89], v124, s[66:67]
	global_load_dwordx4 v[90:93], v124, s[68:69]
	global_load_dwordx4 v[94:97], v124, s[70:71]
	v_add_u32_e32 v124, s36, v124
	s_waitcnt lgkmcnt(3)
	v_mfma_f32_16x16x32_bf16 v[138:141], v[98:101], v[10:13], 0
	v_mfma_f32_16x16x32_bf16 v[142:145], v[98:101], v[14:17], 0
	s_waitcnt lgkmcnt(2)
	v_mfma_f32_16x16x32_bf16 v[138:141], v[102:105], v[2:5], v[138:141]
	v_mfma_f32_16x16x32_bf16 v[142:145], v[102:105], v[6:9], v[142:145]
	ds_read_b128 v[98:101], v136 offset:9216
	ds_read_b128 v[102:105], v136 offset:9280
	s_waitcnt lgkmcnt(3)
	v_mfma_f32_16x16x32_bf16 v[146:149], v[106:109], v[10:13], 0
	v_mfma_f32_16x16x32_bf16 v[150:153], v[106:109], v[14:17], 0
	s_waitcnt lgkmcnt(2)
	v_mfma_f32_16x16x32_bf16 v[146:149], v[110:113], v[2:5], v[146:149]
	v_mfma_f32_16x16x32_bf16 v[150:153], v[110:113], v[6:9], v[150:153]
	ds_read_b128 v[106:109], v136 offset:13824
	ds_read_b128 v[110:113], v136 offset:13888
	v_exp_f32_e32 v138, v138
	v_exp_f32_e32 v139, v139
	v_exp_f32_e32 v140, v140
	v_exp_f32_e32 v141, v141
	v_exp_f32_e32 v142, v142
	v_exp_f32_e32 v143, v143
	v_exp_f32_e32 v144, v144
	v_exp_f32_e32 v145, v145
	v_add_f32_e32 v123, v138, v123
	v_add_f32_e32 v122, v142, v122
	v_add_f32_e32 v123, v139, v123
	v_add_f32_e32 v122, v143, v122
	v_add_f32_e32 v123, v140, v123
	v_add_f32_e32 v122, v144, v122
	v_add_f32_e32 v123, v141, v123
	v_add_f32_e32 v122, v145, v122
	s_waitcnt lgkmcnt(3)
	v_mfma_f32_16x16x32_bf16 v[154:157], v[98:101], v[10:13], 0
	v_exp_f32_e32 v146, v146
	v_exp_f32_e32 v147, v147
	v_mfma_f32_16x16x32_bf16 v[158:161], v[98:101], v[14:17], 0
	v_exp_f32_e32 v148, v148
	v_exp_f32_e32 v149, v149
	s_waitcnt lgkmcnt(2)
	v_mfma_f32_16x16x32_bf16 v[154:157], v[102:105], v[2:5], v[154:157]
	v_exp_f32_e32 v150, v150
	v_exp_f32_e32 v151, v151
	v_mfma_f32_16x16x32_bf16 v[158:161], v[102:105], v[6:9], v[158:161]
	v_exp_f32_e32 v152, v152
	v_exp_f32_e32 v153, v153
	v_cvt_pk_bf16_f32 v114, v138, v139
	v_cvt_pk_bf16_f32 v115, v140, v141
	v_cvt_pk_bf16_f32 v118, v142, v143
	v_cvt_pk_bf16_f32 v119, v144, v145
	ds_read_b128 v[138:141], v170 offset:0
	ds_read_b128 v[142:145], v170 offset:4608
	s_waitcnt lgkmcnt(3)
	v_mfma_f32_16x16x32_bf16 v[162:165], v[106:109], v[10:13], 0
	v_add_f32_e32 v123, v146, v123
	v_add_f32_e32 v122, v150, v122
	v_add_f32_e32 v123, v147, v123
	v_mfma_f32_16x16x32_bf16 v[166:169], v[106:109], v[14:17], 0
	v_add_f32_e32 v122, v151, v122
	v_add_f32_e32 v123, v148, v123
	v_add_f32_e32 v122, v152, v122
	s_waitcnt lgkmcnt(2)
	v_mfma_f32_16x16x32_bf16 v[162:165], v[110:113], v[2:5], v[162:165]
	v_add_f32_e32 v123, v149, v123
	v_add_f32_e32 v122, v153, v122
	v_cvt_pk_bf16_f32 v116, v146, v147
	v_cvt_pk_bf16_f32 v117, v148, v149
	v_mfma_f32_16x16x32_bf16 v[166:169], v[110:113], v[6:9], v[166:169]
	v_cvt_pk_bf16_f32 v120, v150, v151
	v_cvt_pk_bf16_f32 v121, v152, v153
	ds_read_b128 v[146:149], v170 offset:9216
	ds_read_b128 v[150:153], v170 offset:13824
	ds_read_b128 v[98:101], v170 offset:18432
	ds_read_b128 v[102:105], v170 offset:23040
	ds_read_b128 v[106:109], v170 offset:27648
	ds_read_b128 v[110:113], v170 offset:32256
	v_exp_f32_e32 v154, v154
	v_exp_f32_e32 v155, v155
	v_exp_f32_e32 v156, v156
	v_exp_f32_e32 v157, v157
	v_exp_f32_e32 v158, v158
	v_exp_f32_e32 v159, v159
	v_exp_f32_e32 v160, v160
	v_exp_f32_e32 v161, v161
	s_waitcnt lgkmcnt(7)
	v_mfma_f32_16x16x32_bf16 v[78:81], v[138:141], v[114:117], v[78:81]
	v_mfma_f32_16x16x32_bf16 v[74:77], v[138:141], v[118:121], v[74:77]
	v_exp_f32_e32 v162, v162
	v_exp_f32_e32 v163, v163
	v_exp_f32_e32 v164, v164
	v_exp_f32_e32 v165, v165
	s_waitcnt lgkmcnt(6)
	v_mfma_f32_16x16x32_bf16 v[70:73], v[142:145], v[114:117], v[70:73]
	v_mfma_f32_16x16x32_bf16 v[62:65], v[142:145], v[118:121], v[62:65]
	v_exp_f32_e32 v166, v166
	v_exp_f32_e32 v167, v167
	v_exp_f32_e32 v168, v168
	v_exp_f32_e32 v169, v169
	s_waitcnt lgkmcnt(5)
	v_mfma_f32_16x16x32_bf16 v[66:69], v[146:149], v[114:117], v[66:69]
	v_mfma_f32_16x16x32_bf16 v[46:49], v[146:149], v[118:121], v[46:49]
	v_add_f32_e32 v123, v154, v123
	v_add_f32_e32 v122, v158, v122
	v_add_f32_e32 v123, v155, v123
	v_add_f32_e32 v122, v159, v122
	v_add_f32_e32 v123, v156, v123
	v_add_f32_e32 v122, v160, v122
	v_add_f32_e32 v123, v157, v123
	v_add_f32_e32 v122, v161, v122
	s_waitcnt lgkmcnt(4)
	v_mfma_f32_16x16x32_bf16 v[58:61], v[150:153], v[114:117], v[58:61]
	v_mfma_f32_16x16x32_bf16 v[38:41], v[150:153], v[118:121], v[38:41]
	ds_read_b128 v[138:141], v170 offset:18496
	ds_read_b128 v[142:145], v170 offset:23104
	ds_read_b128 v[146:149], v170 offset:27712
	ds_read_b128 v[150:153], v170 offset:32320
	v_cvt_pk_bf16_f32 v184, v154, v155
	v_cvt_pk_bf16_f32 v185, v156, v157
	v_cvt_pk_bf16_f32 v128, v158, v159
	v_cvt_pk_bf16_f32 v129, v160, v161
	s_waitcnt lgkmcnt(7)
	v_mfma_f32_16x16x32_bf16 v[54:57], v[98:101], v[114:117], v[54:57]
	v_mfma_f32_16x16x32_bf16 v[30:33], v[98:101], v[118:121], v[30:33]
	v_add_f32_e32 v123, v162, v123
	v_add_f32_e32 v122, v166, v122
	v_add_f32_e32 v123, v163, v123
	v_add_f32_e32 v122, v167, v122
	v_add_f32_e32 v123, v164, v123
	v_add_f32_e32 v122, v168, v122
	v_add_f32_e32 v123, v165, v123
	v_add_f32_e32 v122, v169, v122
	s_waitcnt lgkmcnt(6)
	v_mfma_f32_16x16x32_bf16 v[50:53], v[102:105], v[114:117], v[50:53]
	v_mfma_f32_16x16x32_bf16 v[26:29], v[102:105], v[118:121], v[26:29]
	v_cvt_pk_bf16_f32 v186, v162, v163
	v_cvt_pk_bf16_f32 v187, v164, v165
	v_cvt_pk_bf16_f32 v130, v166, v167
	v_cvt_pk_bf16_f32 v131, v168, v169
	ds_read_b128 v[154:157], v170 offset:64
	ds_read_b128 v[158:161], v170 offset:4672
	ds_read_b128 v[162:165], v170 offset:9280
	ds_read_b128 v[166:169], v170 offset:13888
	s_waitcnt lgkmcnt(9)
	v_mfma_f32_16x16x32_bf16 v[42:45], v[106:109], v[114:117], v[42:45]
	v_mfma_f32_16x16x32_bf16 v[22:25], v[106:109], v[118:121], v[22:25]
	s_waitcnt lgkmcnt(8)
	v_mfma_f32_16x16x32_bf16 v[34:37], v[110:113], v[114:117], v[34:37]
	v_mfma_f32_16x16x32_bf16 v[18:21], v[110:113], v[118:121], v[18:21]
	ds_read_b128 v[98:101], v136 offset:18432
	ds_read_b128 v[102:105], v136 offset:18496
	ds_read_b128 v[106:109], v136 offset:23040
	ds_read_b128 v[110:113], v136 offset:23104
	s_waitcnt lgkmcnt(7)
	v_mfma_f32_16x16x32_bf16 v[78:81], v[154:157], v[184:187], v[78:81]
	v_mfma_f32_16x16x32_bf16 v[74:77], v[154:157], v[128:131], v[74:77]
	s_waitcnt lgkmcnt(6)
	v_mfma_f32_16x16x32_bf16 v[70:73], v[158:161], v[184:187], v[70:73]
	v_mfma_f32_16x16x32_bf16 v[62:65], v[158:161], v[128:131], v[62:65]
	s_waitcnt vmcnt(3)
	ds_write_b128 v171, v[82:85] offset:0
	s_waitcnt vmcnt(2)
	ds_write_b128 v171, v[86:89] offset:9216
	s_waitcnt vmcnt(1)
	ds_write_b128 v171, v[90:93] offset:18432
	s_waitcnt vmcnt(0)
	ds_write_b128 v171, v[94:97] offset:27648
	s_waitcnt lgkmcnt(9)
	v_mfma_f32_16x16x32_bf16 v[66:69], v[162:165], v[184:187], v[66:69]
	v_mfma_f32_16x16x32_bf16 v[46:49], v[162:165], v[128:131], v[46:49]
	s_waitcnt lgkmcnt(8)
	v_mfma_f32_16x16x32_bf16 v[58:61], v[166:169], v[184:187], v[58:61]
	v_mfma_f32_16x16x32_bf16 v[38:41], v[166:169], v[128:131], v[38:41]
	global_load_dwordx4 v[82:85], v125, s[72:73]
	global_load_dwordx4 v[86:89], v125, s[74:75]
	global_load_dwordx4 v[90:93], v125, s[76:77]
	global_load_dwordx4 v[94:97], v125, s[78:79]
	v_add_u32_e32 v125, s38, v125
	v_mfma_f32_16x16x32_bf16 v[54:57], v[138:141], v[184:187], v[54:57]
	v_mfma_f32_16x16x32_bf16 v[30:33], v[138:141], v[128:131], v[30:33]
	v_mfma_f32_16x16x32_bf16 v[50:53], v[142:145], v[184:187], v[50:53]
	v_mfma_f32_16x16x32_bf16 v[26:29], v[142:145], v[128:131], v[26:29]
	v_mfma_f32_16x16x32_bf16 v[42:45], v[146:149], v[184:187], v[42:45]
	v_mfma_f32_16x16x32_bf16 v[22:25], v[146:149], v[128:131], v[22:25]
	v_mfma_f32_16x16x32_bf16 v[34:37], v[150:153], v[184:187], v[34:37]
	v_mfma_f32_16x16x32_bf16 v[18:21], v[150:153], v[128:131], v[18:21]
	s_waitcnt lgkmcnt(7)
	v_mfma_f32_16x16x32_bf16 v[138:141], v[98:101], v[10:13], 0
	v_mfma_f32_16x16x32_bf16 v[142:145], v[98:101], v[14:17], 0
	s_waitcnt lgkmcnt(6)
	v_mfma_f32_16x16x32_bf16 v[138:141], v[102:105], v[2:5], v[138:141]
	v_mfma_f32_16x16x32_bf16 v[142:145], v[102:105], v[6:9], v[142:145]
	ds_read_b128 v[98:101], v136 offset:27648
	ds_read_b128 v[102:105], v136 offset:27712
	s_waitcnt lgkmcnt(7)
	v_mfma_f32_16x16x32_bf16 v[146:149], v[106:109], v[10:13], 0
	v_mfma_f32_16x16x32_bf16 v[150:153], v[106:109], v[14:17], 0
	s_waitcnt lgkmcnt(6)
	v_mfma_f32_16x16x32_bf16 v[146:149], v[110:113], v[2:5], v[146:149]
	v_mfma_f32_16x16x32_bf16 v[150:153], v[110:113], v[6:9], v[150:153]
	ds_read_b128 v[106:109], v136 offset:32256
	ds_read_b128 v[110:113], v136 offset:32320
	v_exp_f32_e32 v138, v138
	v_exp_f32_e32 v139, v139
	v_exp_f32_e32 v140, v140
	v_exp_f32_e32 v141, v141
	v_exp_f32_e32 v142, v142
	v_exp_f32_e32 v143, v143
	v_exp_f32_e32 v144, v144
	v_exp_f32_e32 v145, v145
	v_add_f32_e32 v123, v138, v123
	v_add_f32_e32 v122, v142, v122
	v_add_f32_e32 v123, v139, v123
	v_add_f32_e32 v122, v143, v122
	v_add_f32_e32 v123, v140, v123
	v_add_f32_e32 v122, v144, v122
	v_add_f32_e32 v123, v141, v123
	v_add_f32_e32 v122, v145, v122
	s_waitcnt lgkmcnt(3)
	v_mfma_f32_16x16x32_bf16 v[154:157], v[98:101], v[10:13], 0
	v_exp_f32_e32 v146, v146
	v_exp_f32_e32 v147, v147
	v_mfma_f32_16x16x32_bf16 v[158:161], v[98:101], v[14:17], 0
	v_exp_f32_e32 v148, v148
	v_exp_f32_e32 v149, v149
	s_waitcnt lgkmcnt(2)
	v_mfma_f32_16x16x32_bf16 v[154:157], v[102:105], v[2:5], v[154:157]
	v_exp_f32_e32 v150, v150
	v_exp_f32_e32 v151, v151
	v_mfma_f32_16x16x32_bf16 v[158:161], v[102:105], v[6:9], v[158:161]
	v_exp_f32_e32 v152, v152
	v_exp_f32_e32 v153, v153
	v_cvt_pk_bf16_f32 v114, v138, v139
	v_cvt_pk_bf16_f32 v115, v140, v141
	v_cvt_pk_bf16_f32 v118, v142, v143
	v_cvt_pk_bf16_f32 v119, v144, v145
	ds_read_b128 v[138:141], v170 offset:128
	ds_read_b128 v[142:145], v170 offset:4736
	s_waitcnt lgkmcnt(3)
	v_mfma_f32_16x16x32_bf16 v[162:165], v[106:109], v[10:13], 0
	v_add_f32_e32 v123, v146, v123
	v_add_f32_e32 v122, v150, v122
	v_add_f32_e32 v123, v147, v123
	v_mfma_f32_16x16x32_bf16 v[166:169], v[106:109], v[14:17], 0
	v_add_f32_e32 v122, v151, v122
	v_add_f32_e32 v123, v148, v123
	v_add_f32_e32 v122, v152, v122
	s_waitcnt lgkmcnt(2)
	v_mfma_f32_16x16x32_bf16 v[162:165], v[110:113], v[2:5], v[162:165]
	v_add_f32_e32 v123, v149, v123
	v_add_f32_e32 v122, v153, v122
	v_cvt_pk_bf16_f32 v116, v146, v147
	v_cvt_pk_bf16_f32 v117, v148, v149
	v_mfma_f32_16x16x32_bf16 v[166:169], v[110:113], v[6:9], v[166:169]
	v_cvt_pk_bf16_f32 v120, v150, v151
	v_cvt_pk_bf16_f32 v121, v152, v153
	ds_read_b128 v[146:149], v170 offset:9344
	ds_read_b128 v[150:153], v170 offset:13952
	ds_read_b128 v[98:101], v170 offset:18560
	ds_read_b128 v[102:105], v170 offset:23168
	ds_read_b128 v[106:109], v170 offset:27776
	ds_read_b128 v[110:113], v170 offset:32384
	v_exp_f32_e32 v154, v154
	v_exp_f32_e32 v155, v155
	v_exp_f32_e32 v156, v156
	v_exp_f32_e32 v157, v157
	v_exp_f32_e32 v158, v158
	v_exp_f32_e32 v159, v159
	v_exp_f32_e32 v160, v160
	v_exp_f32_e32 v161, v161
	s_waitcnt lgkmcnt(7)
	v_mfma_f32_16x16x32_bf16 v[78:81], v[138:141], v[114:117], v[78:81]
	v_mfma_f32_16x16x32_bf16 v[74:77], v[138:141], v[118:121], v[74:77]
	v_exp_f32_e32 v162, v162
	v_exp_f32_e32 v163, v163
	v_exp_f32_e32 v164, v164
	v_exp_f32_e32 v165, v165
	s_waitcnt lgkmcnt(6)
	v_mfma_f32_16x16x32_bf16 v[70:73], v[142:145], v[114:117], v[70:73]
	v_mfma_f32_16x16x32_bf16 v[62:65], v[142:145], v[118:121], v[62:65]
	v_exp_f32_e32 v166, v166
	v_exp_f32_e32 v167, v167
	v_exp_f32_e32 v168, v168
	v_exp_f32_e32 v169, v169
	s_waitcnt lgkmcnt(5)
	v_mfma_f32_16x16x32_bf16 v[66:69], v[146:149], v[114:117], v[66:69]
	v_mfma_f32_16x16x32_bf16 v[46:49], v[146:149], v[118:121], v[46:49]
	v_add_f32_e32 v123, v154, v123
	v_add_f32_e32 v122, v158, v122
	v_add_f32_e32 v123, v155, v123
	v_add_f32_e32 v122, v159, v122
	v_add_f32_e32 v123, v156, v123
	v_add_f32_e32 v122, v160, v122
	v_add_f32_e32 v123, v157, v123
	v_add_f32_e32 v122, v161, v122
	s_waitcnt lgkmcnt(4)
	v_mfma_f32_16x16x32_bf16 v[58:61], v[150:153], v[114:117], v[58:61]
	v_mfma_f32_16x16x32_bf16 v[38:41], v[150:153], v[118:121], v[38:41]
	ds_read_b128 v[138:141], v170 offset:18624
	ds_read_b128 v[142:145], v170 offset:23232
	ds_read_b128 v[146:149], v170 offset:27840
	ds_read_b128 v[150:153], v170 offset:32448
	v_cvt_pk_bf16_f32 v184, v154, v155
	v_cvt_pk_bf16_f32 v185, v156, v157
	v_cvt_pk_bf16_f32 v128, v158, v159
	v_cvt_pk_bf16_f32 v129, v160, v161
	s_waitcnt lgkmcnt(7)
	v_mfma_f32_16x16x32_bf16 v[54:57], v[98:101], v[114:117], v[54:57]
	v_mfma_f32_16x16x32_bf16 v[30:33], v[98:101], v[118:121], v[30:33]
	v_add_f32_e32 v123, v162, v123
	v_add_f32_e32 v122, v166, v122
	v_add_f32_e32 v123, v163, v123
	v_add_f32_e32 v122, v167, v122
	v_add_f32_e32 v123, v164, v123
	v_add_f32_e32 v122, v168, v122
	v_add_f32_e32 v123, v165, v123
	v_add_f32_e32 v122, v169, v122
	s_waitcnt lgkmcnt(6)
	v_mfma_f32_16x16x32_bf16 v[50:53], v[102:105], v[114:117], v[50:53]
	v_mfma_f32_16x16x32_bf16 v[26:29], v[102:105], v[118:121], v[26:29]
	v_cvt_pk_bf16_f32 v186, v162, v163
	v_cvt_pk_bf16_f32 v187, v164, v165
	v_cvt_pk_bf16_f32 v130, v166, v167
	v_cvt_pk_bf16_f32 v131, v168, v169
	ds_read_b128 v[154:157], v170 offset:192
	ds_read_b128 v[158:161], v170 offset:4800
	ds_read_b128 v[162:165], v170 offset:9408
	ds_read_b128 v[166:169], v170 offset:14016
	s_waitcnt lgkmcnt(9)
	v_mfma_f32_16x16x32_bf16 v[42:45], v[106:109], v[114:117], v[42:45]
	v_mfma_f32_16x16x32_bf16 v[22:25], v[106:109], v[118:121], v[22:25]
	s_waitcnt lgkmcnt(8)
	v_mfma_f32_16x16x32_bf16 v[34:37], v[110:113], v[114:117], v[34:37]
	v_mfma_f32_16x16x32_bf16 v[18:21], v[110:113], v[118:121], v[18:21]
	s_waitcnt lgkmcnt(3)
	v_mfma_f32_16x16x32_bf16 v[78:81], v[154:157], v[184:187], v[78:81]
	v_mfma_f32_16x16x32_bf16 v[74:77], v[154:157], v[128:131], v[74:77]
	s_waitcnt lgkmcnt(2)
	v_mfma_f32_16x16x32_bf16 v[70:73], v[158:161], v[184:187], v[70:73]
	v_mfma_f32_16x16x32_bf16 v[62:65], v[158:161], v[128:131], v[62:65]
	s_waitcnt lgkmcnt(1)
	v_mfma_f32_16x16x32_bf16 v[66:69], v[162:165], v[184:187], v[66:69]
	v_mfma_f32_16x16x32_bf16 v[46:49], v[162:165], v[128:131], v[46:49]
	s_waitcnt lgkmcnt(0)
	v_mfma_f32_16x16x32_bf16 v[58:61], v[166:169], v[184:187], v[58:61]
	v_mfma_f32_16x16x32_bf16 v[38:41], v[166:169], v[128:131], v[38:41]
	s_waitcnt vmcnt(3)
	ds_write_b128 v173, v[82:85] offset:0
	s_waitcnt vmcnt(2)
	ds_write_b128 v173, v[86:89] offset:9216
	s_waitcnt vmcnt(1)
	ds_write_b128 v173, v[90:93] offset:18432
	s_waitcnt vmcnt(0)
	ds_write_b128 v173, v[94:97] offset:27648
	v_mfma_f32_16x16x32_bf16 v[54:57], v[138:141], v[184:187], v[54:57]
	v_mfma_f32_16x16x32_bf16 v[30:33], v[138:141], v[128:131], v[30:33]
	v_mfma_f32_16x16x32_bf16 v[50:53], v[142:145], v[184:187], v[50:53]
	v_mfma_f32_16x16x32_bf16 v[26:29], v[142:145], v[128:131], v[26:29]
	v_mfma_f32_16x16x32_bf16 v[42:45], v[146:149], v[184:187], v[42:45]
	v_mfma_f32_16x16x32_bf16 v[22:25], v[146:149], v[128:131], v[22:25]
	v_mfma_f32_16x16x32_bf16 v[34:37], v[150:153], v[184:187], v[34:37]
	v_mfma_f32_16x16x32_bf16 v[18:21], v[150:153], v[128:131], v[18:21]
	s_waitcnt lgkmcnt(0)
	s_barrier
	s_add_i32 s15, s15, 1
	s_cmp_eq_u32 s15, 33
	s_cbranch_scc0 .Lattn_nf_loop
	v_readlane_b32 s64, v175, 0
	v_readlane_b32 s65, v175, 1
	v_readlane_b32 s66, v175, 2
	v_readlane_b32 s67, v175, 3
	v_readlane_b32 s68, v175, 4
	v_readlane_b32 s69, v175, 5
	v_readlane_b32 s70, v175, 6
	v_readlane_b32 s71, v175, 7
	v_readlane_b32 s72, v175, 8
	v_readlane_b32 s73, v175, 9
	v_readlane_b32 s74, v175, 10
	v_readlane_b32 s75, v175, 11
	v_readlane_b32 s76, v175, 12
	v_readlane_b32 s77, v175, 13
	v_readlane_b32 s78, v175, 14
	v_readlane_b32 s79, v175, 15
	s_nop 4
	v_add_u32_e32 v216, 0x9000, v137
	v_add_u32_e32 v217, 0x9000, v183
	ds_read_b128 v[82:85], v216 offset:0
	ds_read_b128 v[90:93], v216 offset:64
	v_add_f32_e32 v186, v132, v134
	v_add_f32_e32 v184, v133, v135
	ds_bpermute_b32 v187, v172, v186
	ds_bpermute_b32 v185, v172, v184
	s_mov_b32 s10, 0x3fb8aa3b
	s_mov_b32 s11, 0xc2ce8ed0
	s_mov_b32 s6, 0x42b17218
	s_waitcnt lgkmcnt(3)
	v_mfma_f32_16x16x32_bf16 v[86:89], v[82:85], v[10:13], 0
	v_cmp_eq_u32_e64 s[40:41], 0, v179
	s_lshl_b32 s30, s14, 1
	v_lshlrev_b32_e32 v196, 3, v178
	v_mov_b32_e32 v197, 0
	v_lshlrev_b32_e32 v198, 4, v179
	v_or3_b32 v198, v198, v177, v180
	v_ashrrev_i32_e32 v199, 31, v198
	v_lshlrev_b64 v[198:199], 11, v[198:199]
	s_mov_b64 s[100:101], 0x18a10000
	v_lshl_add_u64 v[198:199], s[42:43], 0, v[198:199]
	v_lshl_add_u64 v[198:199], v[198:199], 0, s[30:31]
	v_lshl_add_u64 v[198:199], v[198:199], 0, v[196:197]
	v_lshl_add_u64 v[198:199], v[198:199], 0, s[100:101]
	global_load_dwordx2 v[146:147], v[198:199], off
	global_load_dwordx2 v[148:149], v[198:199], off offset:32
	global_load_dwordx2 v[150:151], v[198:199], off offset:64
	global_load_dwordx2 v[152:153], v[198:199], off offset:96
	global_load_dwordx2 v[188:189], v[198:199], off offset:128
	global_load_dwordx2 v[190:191], v[198:199], off offset:160
	global_load_dwordx2 v[192:193], v[198:199], off offset:192
	global_load_dwordx2 v[194:195], v[198:199], off offset:224
	s_mov_b64 s[100:101], exec
	s_and_b64 exec, exec, s[4:5]
	s_cbranch_execz .Lpop_skip
	v_readlane_b32 s14, v255, 22
	v_readlane_b32 s15, v255, 23
	v_mov_b32_e32 v224, 1
	s_nop 4
	global_atomic_add v224, v0, v224, s[14:15] sc0
.Lpop_skip:
	s_mov_b64 exec, s[100:101]
	v_mov_b32_e32 v235, 1
	s_load_dwordx2 s[100:101], s[44:45], 0x80
	v_readlane_b32 s14, v255, 36
	v_mfma_f32_16x16x32_bf16 v[82:85], v[82:85], v[14:17], 0
	ds_read_b128 v[98:101], v216 offset:4672
	v_readlane_b32 s15, v255, 37
	s_lshl_b64 s[14:15], s[14:15], 2
	s_waitcnt lgkmcnt(3)
	v_mfma_f32_16x16x32_bf16 v[86:89], v[90:93], v[2:5], v[86:89]
	ds_read_b128 v[142:145], v216 offset:13888
	v_mfma_f32_16x16x32_bf16 v[82:85], v[90:93], v[6:9], v[82:85]
	ds_read_b128 v[90:93], v216 offset:4608
	s_nop 4
	v_exp_f32_e32 v116, v86
	v_exp_f32_e32 v114, v87
	s_waitcnt lgkmcnt(0)
	v_mfma_f32_16x16x32_bf16 v[94:97], v[90:93], v[10:13], 0
	v_exp_f32_e32 v134, v82
	v_exp_f32_e32 v132, v83
	v_exp_f32_e32 v130, v84
	v_mfma_f32_16x16x32_bf16 v[90:93], v[90:93], v[14:17], 0
	v_exp_f32_e32 v128, v85
	ds_read_b128 v[82:85], v216 offset:9216
	v_exp_f32_e32 v112, v88
	v_mfma_f32_16x16x32_bf16 v[90:93], v[98:101], v[6:9], v[90:93]
	v_exp_f32_e32 v110, v89
	v_mfma_f32_16x16x32_bf16 v[94:97], v[98:101], v[2:5], v[94:97]
	s_nop 1
	v_cvt_pk_bf16_f32 v98, v134, v132
	s_nop 1
	s_nop 5
	v_exp_f32_e32 v126, v90
	v_exp_f32_e32 v124, v91
	v_exp_f32_e32 v120, v92
	v_exp_f32_e32 v118, v93
	ds_read_b128 v[90:93], v216 offset:9280
	s_waitcnt lgkmcnt(1)
	v_mfma_f32_16x16x32_bf16 v[86:89], v[82:85], v[10:13], 0
	v_exp_f32_e32 v108, v94
	v_exp_f32_e32 v106, v95
	v_exp_f32_e32 v104, v96
	v_mfma_f32_16x16x32_bf16 v[82:85], v[82:85], v[14:17], 0
	v_exp_f32_e32 v102, v97
	s_nop 1
	v_cvt_pk_bf16_f32 v94, v116, v114
	s_nop 1
	s_nop 1
	v_cvt_pk_bf16_f32 v95, v112, v110
	s_nop 1
	s_waitcnt lgkmcnt(0)
	v_mfma_f32_16x16x32_bf16 v[82:85], v[90:93], v[6:9], v[82:85]
	s_nop 1
	v_cvt_pk_bf16_f32 v96, v108, v106
	s_nop 1
	s_nop 1
	v_cvt_pk_bf16_f32 v97, v104, v102
	s_nop 1
	s_nop 1
	v_cvt_pk_bf16_f32 v99, v130, v128
	s_nop 1
	v_mfma_f32_16x16x32_bf16 v[86:89], v[90:93], v[2:5], v[86:89]
	ds_read_b128 v[90:93], v216 offset:13824
	s_nop 5
	v_exp_f32_e32 v135, v82
	v_exp_f32_e32 v133, v83
	v_exp_f32_e32 v131, v84
	v_exp_f32_e32 v129, v85
	ds_read_b128 v[82:85], v217 offset:0
	s_nop 1
	v_cvt_pk_bf16_f32 v100, v126, v124
	s_nop 1
	s_nop 1
	v_cvt_pk_bf16_f32 v101, v120, v118
	s_nop 1
	s_waitcnt lgkmcnt(0)
	v_mfma_f32_16x16x32_bf16 v[78:81], v[82:85], v[94:97], v[78:81]
	v_exp_f32_e32 v117, v86
	v_exp_f32_e32 v115, v87
	v_exp_f32_e32 v113, v88
	v_mfma_f32_16x16x32_bf16 v[74:77], v[82:85], v[98:101], v[74:77]
	ds_read_b128 v[82:85], v217 offset:64
	v_exp_f32_e32 v111, v89
	v_mfma_f32_16x16x32_bf16 v[138:141], v[90:93], v[10:13], 0
	v_mfma_f32_16x16x32_bf16 v[90:93], v[90:93], v[14:17], 0
	v_mfma_f32_16x16x32_bf16 v[90:93], v[142:145], v[6:9], v[90:93]
	v_mfma_f32_16x16x32_bf16 v[138:141], v[142:145], v[2:5], v[138:141]
	s_nop 1
	v_cvt_pk_bf16_f32 v142, v135, v133
	s_nop 1
	s_nop 6
	v_exp_f32_e32 v127, v90
	v_exp_f32_e32 v125, v91
	v_exp_f32_e32 v121, v92
	v_exp_f32_e32 v119, v93
	s_nop 1
	v_cvt_pk_bf16_f32 v143, v131, v129
	s_nop 1
	s_nop 1
	v_cvt_pk_bf16_f32 v144, v127, v125
	s_nop 1
	s_nop 1
	v_cvt_pk_bf16_f32 v145, v121, v119
	s_nop 1
	v_exp_f32_e32 v109, v138
	s_waitcnt lgkmcnt(0)
	v_mfma_f32_16x16x32_bf16 v[90:93], v[82:85], v[142:145], v[74:77]
	v_exp_f32_e32 v107, v139
	v_exp_f32_e32 v105, v140
	v_exp_f32_e32 v103, v141
	ds_read_b128 v[74:77], v217 offset:4608
	s_waitcnt lgkmcnt(0)
	v_mfma_f32_16x16x32_bf16 v[70:73], v[74:77], v[94:97], v[70:73]
	s_nop 1
	v_cvt_pk_bf16_f32 v138, v117, v115
	s_nop 1
	s_nop 1
	v_cvt_pk_bf16_f32 v139, v113, v111
	s_nop 1
	s_nop 1
	v_cvt_pk_bf16_f32 v140, v109, v107
	s_nop 1
	v_mfma_f32_16x16x32_bf16 v[62:65], v[74:77], v[98:101], v[62:65]
	ds_read_b128 v[74:77], v217 offset:4672
	s_nop 1
	v_cvt_pk_bf16_f32 v141, v105, v103
	s_nop 1
	s_waitcnt lgkmcnt(0)
	v_mfma_f32_16x16x32_bf16 v[86:89], v[74:77], v[142:145], v[62:65]
	s_nop 4
	ds_read_b128 v[62:65], v217 offset:9216
	s_waitcnt lgkmcnt(0)
	v_mfma_f32_16x16x32_bf16 v[66:69], v[62:65], v[94:97], v[66:69]
	v_mfma_f32_16x16x32_bf16 v[46:49], v[62:65], v[98:101], v[46:49]
	ds_read_b128 v[62:65], v217 offset:9280
	v_mfma_f32_16x16x32_bf16 v[78:81], v[82:85], v[138:141], v[78:81]
	v_mfma_f32_16x16x32_bf16 v[82:85], v[74:77], v[138:141], v[70:73]
	s_waitcnt lgkmcnt(0)
	v_mfma_f32_16x16x32_bf16 v[74:77], v[62:65], v[142:145], v[46:49]
	s_nop 2
	ds_read_b128 v[46:49], v217 offset:13824
	s_waitcnt lgkmcnt(0)
	v_mfma_f32_16x16x32_bf16 v[58:61], v[46:49], v[94:97], v[58:61]
	v_mfma_f32_16x16x32_bf16 v[38:41], v[46:49], v[98:101], v[38:41]
	ds_read_b128 v[46:49], v217 offset:13888
	v_mfma_f32_16x16x32_bf16 v[70:73], v[62:65], v[138:141], v[66:69]
	s_waitcnt lgkmcnt(0)
	v_mfma_f32_16x16x32_bf16 v[66:69], v[46:49], v[142:145], v[38:41]
	s_nop 3
	ds_read_b128 v[38:41], v217 offset:18432
	v_mfma_f32_16x16x32_bf16 v[62:65], v[46:49], v[138:141], v[58:61]
	s_waitcnt lgkmcnt(0)
	v_mfma_f32_16x16x32_bf16 v[46:49], v[38:41], v[94:97], v[54:57]
	v_mfma_f32_16x16x32_bf16 v[30:33], v[38:41], v[98:101], v[30:33]
	ds_read_b128 v[38:41], v217 offset:18496
	s_waitcnt lgkmcnt(0)
	v_mfma_f32_16x16x32_bf16 v[58:61], v[38:41], v[142:145], v[30:33]
	s_nop 4
	ds_read_b128 v[30:33], v217 offset:23040
	v_mfma_f32_16x16x32_bf16 v[54:57], v[38:41], v[138:141], v[46:49]
	s_waitcnt lgkmcnt(0)
	v_mfma_f32_16x16x32_bf16 v[38:41], v[30:33], v[94:97], v[50:53]
	s_nop 2
	ds_read_b128 v[50:53], v216 offset:18496
	v_mfma_f32_16x16x32_bf16 v[26:29], v[30:33], v[98:101], v[26:29]
	ds_read_b128 v[30:33], v217 offset:23104
	s_waitcnt lgkmcnt(0)
	v_mfma_f32_16x16x32_bf16 v[46:49], v[30:33], v[142:145], v[26:29]
	s_nop 4
	ds_read_b128 v[26:29], v217 offset:27648
	v_mfma_f32_16x16x32_bf16 v[38:41], v[30:33], v[138:141], v[38:41]
	s_waitcnt lgkmcnt(0)
	v_mfma_f32_16x16x32_bf16 v[30:33], v[26:29], v[94:97], v[42:45]
	s_nop 2
	ds_read_b128 v[42:45], v217 offset:27712
	v_mfma_f32_16x16x32_bf16 v[22:25], v[26:29], v[98:101], v[22:25]
	s_waitcnt lgkmcnt(0)
	v_mfma_f32_16x16x32_bf16 v[26:29], v[42:45], v[138:141], v[30:33]
	v_mfma_f32_16x16x32_bf16 v[30:33], v[42:45], v[142:145], v[22:25]
	ds_read_b128 v[42:45], v217 offset:32320
	s_nop 3
	ds_read_b128 v[22:25], v217 offset:32256
	s_waitcnt lgkmcnt(0)
	v_mfma_f32_16x16x32_bf16 v[34:37], v[22:25], v[94:97], v[34:37]
	v_mfma_f32_16x16x32_bf16 v[22:25], v[22:25], v[98:101], v[18:21]
	ds_read_b128 v[98:101], v216 offset:23104
	v_mfma_f32_16x16x32_bf16 v[18:21], v[42:45], v[138:141], v[34:37]
	s_nop 4
	ds_read_b128 v[34:37], v216 offset:18432
	v_mfma_f32_16x16x32_bf16 v[22:25], v[42:45], v[142:145], v[22:25]
	s_waitcnt lgkmcnt(0)
	v_mfma_f32_16x16x32_bf16 v[42:45], v[34:37], v[10:13], 0
	v_mfma_f32_16x16x32_bf16 v[34:37], v[34:37], v[14:17], 0
	v_mfma_f32_16x16x32_bf16 v[42:45], v[50:53], v[2:5], v[42:45]
	v_mfma_f32_16x16x32_bf16 v[34:37], v[50:53], v[6:9], v[34:37]
	ds_read_b128 v[50:53], v216 offset:23040
	s_nop 5
	v_exp_f32_e32 v158, v42
	v_exp_f32_e32 v156, v43
	s_waitcnt lgkmcnt(0)
	v_mfma_f32_16x16x32_bf16 v[94:97], v[50:53], v[10:13], 0
	v_exp_f32_e32 v172, v34
	v_exp_f32_e32 v174, v35
	v_pk_add_f32 v[34:35], v[134:135], 0 op_sel_hi:[1,0]
	v_mfma_f32_16x16x32_bf16 v[50:53], v[50:53], v[14:17], 0
	v_add_f32_e64 v34, v132, v34
	v_add_f32_e64 v35, v133, v35
	v_exp_f32_e32 v170, v36
	v_pk_add_f32 v[34:35], v[130:131], v[34:35]
	v_mfma_f32_16x16x32_bf16 v[50:53], v[98:101], v[6:9], v[50:53]
	v_add_f32_e64 v34, v128, v34
	v_add_f32_e64 v35, v129, v35
	v_exp_f32_e32 v166, v37
	v_pk_add_f32 v[34:35], v[34:35], v[126:127]
	v_exp_f32_e32 v154, v44
	v_pk_add_f32 v[34:35], v[124:125], v[34:35]
	s_nop 1
	v_exp_f32_e32 v168, v50
	v_pk_add_f32 v[34:35], v[120:121], v[34:35]
	v_exp_f32_e32 v164, v51
	v_pk_add_f32 v[118:119], v[118:119], v[34:35]
	ds_read_b128 v[34:37], v216 offset:27648
	v_exp_f32_e32 v160, v52
	v_exp_f32_e32 v162, v53
	ds_read_b128 v[50:53], v216 offset:27712
	v_exp_f32_e32 v144, v45
	s_waitcnt lgkmcnt(1)
	v_mfma_f32_16x16x32_bf16 v[42:45], v[34:37], v[10:13], 0
	v_mfma_f32_16x16x32_bf16 v[34:37], v[34:37], v[14:17], 0
	s_waitcnt lgkmcnt(0)
	v_mfma_f32_16x16x32_bf16 v[42:45], v[50:53], v[2:5], v[42:45]
	v_mfma_f32_16x16x32_bf16 v[34:37], v[50:53], v[6:9], v[34:37]
	ds_read_b128 v[50:53], v216 offset:32256
	s_nop 5
	v_exp_f32_e32 v159, v42
	v_exp_f32_e32 v157, v43
	s_waitcnt lgkmcnt(0)
	v_mfma_f32_16x16x32_bf16 v[10:13], v[50:53], v[10:13], 0
	v_exp_f32_e32 v173, v34
	v_exp_f32_e32 v175, v35
	v_exp_f32_e32 v171, v36
	v_mfma_f32_16x16x32_bf16 v[14:17], v[50:53], v[14:17], 0
	ds_read_b128 v[50:53], v216 offset:32320
	v_exp_f32_e32 v167, v37
	s_nop 1
	v_cvt_pk_bf16_f32 v128, v173, v175
	s_nop 1
	v_mfma_f32_16x16x32_bf16 v[94:97], v[98:101], v[2:5], v[94:97]
	s_nop 1
	v_cvt_pk_bf16_f32 v98, v172, v174
	s_nop 1
	s_nop 1
	v_cvt_pk_bf16_f32 v99, v170, v166
	s_nop 1
	s_nop 1
	v_cvt_pk_bf16_f32 v100, v168, v164
	s_nop 1
	s_waitcnt lgkmcnt(0)
	v_mfma_f32_16x16x32_bf16 v[2:5], v[50:53], v[2:5], v[10:13]
	s_nop 1
	v_cvt_pk_bf16_f32 v101, v160, v162
	s_nop 1
	s_nop 5
	v_exp_f32_e32 v142, v94
	ds_read_b128 v[10:13], v217 offset:192
	v_exp_f32_e32 v143, v2
	v_exp_f32_e32 v141, v3
	v_exp_f32_e32 v139, v4
	v_exp_f32_e32 v137, v5
	ds_read_b128 v[2:5], v217 offset:128
	v_mfma_f32_16x16x32_bf16 v[6:9], v[50:53], v[6:9], v[14:17]
	v_exp_f32_e32 v140, v95
	v_exp_f32_e32 v138, v96
	v_exp_f32_e32 v136, v97
	s_nop 1
	v_cvt_pk_bf16_f32 v94, v158, v156
	s_nop 1
	s_nop 1
	v_cvt_pk_bf16_f32 v95, v154, v144
	s_nop 1
	s_nop 1
	v_cvt_pk_bf16_f32 v96, v142, v140
	s_nop 1
	s_nop 1
	v_cvt_pk_bf16_f32 v97, v138, v136
	s_nop 1
	s_nop 4
	v_exp_f32_e32 v169, v6
	v_exp_f32_e32 v165, v7
	v_exp_f32_e32 v161, v8
	v_exp_f32_e32 v163, v9
	s_waitcnt lgkmcnt(0)
	v_mfma_f32_16x16x32_bf16 v[6:9], v[2:5], v[94:97], v[78:81]
	s_nop 1
	v_cvt_pk_bf16_f32 v129, v171, v167
	s_nop 1
	s_nop 1
	v_cvt_pk_bf16_f32 v130, v169, v165
	s_nop 1
	s_nop 1
	v_cvt_pk_bf16_f32 v131, v161, v163
	s_nop 1
	v_mfma_f32_16x16x32_bf16 v[2:5], v[2:5], v[98:101], v[90:93]
	v_exp_f32_e32 v155, v44
	v_exp_f32_e32 v145, v45
	s_nop 1
	v_cvt_pk_bf16_f32 v124, v159, v157
	s_nop 1
	v_mfma_f32_16x16x32_bf16 v[90:93], v[10:13], v[128:131], v[2:5]
	s_nop 1
	v_cvt_pk_bf16_f32 v125, v155, v145
	s_nop 1
	s_nop 1
	v_cvt_pk_bf16_f32 v126, v143, v141
	s_nop 1
	s_nop 1
	v_cvt_pk_bf16_f32 v127, v139, v137
	s_nop 1
	s_nop 0
	v_mfma_f32_16x16x32_bf16 v[78:81], v[10:13], v[124:127], v[6:9]
	s_nop 2
	ds_read_b128 v[2:5], v217 offset:4736
	ds_read_b128 v[10:13], v217 offset:4800
	s_waitcnt lgkmcnt(1)
	v_mfma_f32_16x16x32_bf16 v[6:9], v[2:5], v[94:97], v[82:85]
	v_mfma_f32_16x16x32_bf16 v[2:5], v[2:5], v[98:101], v[86:89]
	s_waitcnt lgkmcnt(0)
	v_mfma_f32_16x16x32_bf16 v[50:53], v[10:13], v[128:131], v[2:5]
	v_mfma_f32_16x16x32_bf16 v[14:17], v[10:13], v[124:127], v[6:9]
	s_nop 4
	ds_read_b128 v[2:5], v217 offset:9344
	ds_read_b128 v[10:13], v217 offset:9408
	s_waitcnt lgkmcnt(1)
	v_mfma_f32_16x16x32_bf16 v[6:9], v[2:5], v[94:97], v[70:73]
	v_mfma_f32_16x16x32_bf16 v[2:5], v[2:5], v[98:101], v[74:77]
	s_waitcnt lgkmcnt(0)
	v_mfma_f32_16x16x32_bf16 v[34:37], v[10:13], v[128:131], v[2:5]
	v_mfma_f32_16x16x32_bf16 v[6:9], v[10:13], v[124:127], v[6:9]
	s_nop 4
	ds_read_b128 v[2:5], v217 offset:13952
	s_waitcnt lgkmcnt(0)
	v_mfma_f32_16x16x32_bf16 v[10:13], v[2:5], v[94:97], v[62:65]
	s_nop 2
	ds_read_b128 v[62:65], v217 offset:14016
	v_mfma_f32_16x16x32_bf16 v[42:45], v[2:5], v[98:101], v[66:69]
	s_waitcnt lgkmcnt(0)
	v_mfma_f32_16x16x32_bf16 v[2:5], v[62:65], v[124:127], v[10:13]
	v_mfma_f32_16x16x32_bf16 v[10:13], v[62:65], v[128:131], v[42:45]
	ds_read_b128 v[62:65], v217 offset:18624
	s_nop 3
	ds_read_b128 v[42:45], v217 offset:18560
	s_waitcnt lgkmcnt(0)
	v_mfma_f32_16x16x32_bf16 v[54:57], v[42:45], v[94:97], v[54:57]
	v_mfma_f32_16x16x32_bf16 v[58:61], v[42:45], v[98:101], v[58:61]
	v_mfma_f32_16x16x32_bf16 v[42:45], v[62:65], v[124:127], v[54:57]
	v_mfma_f32_16x16x32_bf16 v[54:57], v[62:65], v[128:131], v[58:61]
	s_nop 5
	ds_read_b128 v[58:61], v217 offset:23168
	s_waitcnt lgkmcnt(0)
	v_mfma_f32_16x16x32_bf16 v[38:41], v[58:61], v[94:97], v[38:41]
	v_mfma_f32_16x16x32_bf16 v[46:49], v[58:61], v[98:101], v[46:49]
	ds_read_b128 v[58:61], v217 offset:23232
	s_waitcnt lgkmcnt(0)
	v_mfma_f32_16x16x32_bf16 v[38:41], v[58:61], v[124:127], v[38:41]
	v_mfma_f32_16x16x32_bf16 v[46:49], v[58:61], v[128:131], v[46:49]
	ds_read_b128 v[58:61], v217 offset:27776
	s_waitcnt lgkmcnt(0)
	v_mfma_f32_16x16x32_bf16 v[26:29], v[58:61], v[94:97], v[26:29]
	v_mfma_f32_16x16x32_bf16 v[30:33], v[58:61], v[98:101], v[30:33]
	ds_read_b128 v[58:61], v217 offset:27840
	s_waitcnt lgkmcnt(0)
	v_mfma_f32_16x16x32_bf16 v[26:29], v[58:61], v[124:127], v[26:29]
	v_mfma_f32_16x16x32_bf16 v[30:33], v[58:61], v[128:131], v[30:33]
	ds_read_b128 v[58:61], v217 offset:32384
	s_waitcnt lgkmcnt(0)
	v_mfma_f32_16x16x32_bf16 v[18:21], v[58:61], v[94:97], v[18:21]
	v_mfma_f32_16x16x32_bf16 v[22:25], v[58:61], v[98:101], v[22:25]
	ds_read_b128 v[58:61], v217 offset:32448
	s_waitcnt lgkmcnt(0)
	s_barrier
	v_mfma_f32_16x16x32_bf16 v[18:21], v[58:61], v[124:127], v[18:21]
	v_mfma_f32_16x16x32_bf16 v[22:25], v[58:61], v[128:131], v[22:25]
	v_add_f32_e64 v58, v172, 0
	v_add_f32_e64 v59, v173, 0
	v_add_f32_e32 v60, v122, v118
	v_pk_add_f32 v[58:59], v[174:175], v[58:59]
	v_add_f32_e32 v60, v60, v119
	v_pk_add_f32 v[58:59], v[170:171], v[58:59]
	s_nop 0
	v_pk_add_f32 v[58:59], v[166:167], v[58:59]
	s_nop 0
	v_pk_add_f32 v[58:59], v[58:59], v[168:169]
	s_nop 0
	v_pk_add_f32 v[58:59], v[164:165], v[58:59]
	s_nop 0
	v_pk_add_f32 v[58:59], v[160:161], v[58:59]
	s_nop 0
	v_pk_add_f32 v[58:59], v[162:163], v[58:59]
	s_nop 0
	v_add_f32_e32 v58, v60, v58
	v_pk_add_f32 v[60:61], v[116:117], 0 op_sel_hi:[1,0]
	v_add_f32_e32 v62, v58, v59
	v_pk_add_f32 v[60:61], v[114:115], v[60:61]
	v_pk_add_f32 v[58:59], v[158:159], 0 op_sel_hi:[1,0]
	v_pk_add_f32 v[60:61], v[112:113], v[60:61]
	v_pk_add_f32 v[58:59], v[156:157], v[58:59]
	v_pk_add_f32 v[60:61], v[110:111], v[60:61]
	v_pk_add_f32 v[58:59], v[154:155], v[58:59]
	v_pk_add_f32 v[60:61], v[60:61], v[108:109]
	v_pk_add_f32 v[58:59], v[144:145], v[58:59]
	v_pk_add_f32 v[60:61], v[106:107], v[60:61]
	v_pk_add_f32 v[58:59], v[58:59], v[142:143]
	v_pk_add_f32 v[60:61], v[104:105], v[60:61]
	v_pk_add_f32 v[58:59], v[140:141], v[58:59]
	v_pk_add_f32 v[60:61], v[102:103], v[60:61]
	v_pk_add_f32 v[58:59], v[138:139], v[58:59]
	v_add_f32_e32 v60, v123, v60
	v_pk_add_f32 v[58:59], v[136:137], v[58:59]
	v_add_f32_e32 v60, v60, v61
	v_add_f32_e32 v58, v60, v58
	v_add_f32_e32 v58, v58, v59
	v_add_f32_e32 v59, v186, v187
	v_mul_f32_e32 v60, 0x3fb8aa3b, v59
	v_fma_f32 v61, v59, s10, -v60
	v_rndne_f32_e32 v63, v60
	v_fmac_f32_e32 v61, 0x32a5705f, v59
	v_sub_f32_e32 v60, v60, v63
	v_add_f32_e32 v60, v60, v61
	v_exp_f32_e32 v60, v60
	v_cvt_i32_f32_e32 v61, v63
	v_cmp_ngt_f32_e32 vcc, s11, v59
	v_ldexp_f32 v60, v60, v61
	s_nop 0
	v_cndmask_b32_e32 v60, 0, v60, vcc
	v_cmp_nlt_f32_e32 vcc, s6, v59
	s_nop 1
	v_cndmask_b32_e32 v59, v220, v60, vcc
	v_add_f32_e32 v60, v184, v185
	v_mul_f32_e32 v61, 0x3fb8aa3b, v60
	v_fma_f32 v63, v60, s10, -v61
	v_rndne_f32_e32 v64, v61
	v_fmac_f32_e32 v63, 0x32a5705f, v60
	v_sub_f32_e32 v61, v61, v64
	v_add_f32_e32 v61, v61, v63
	v_exp_f32_e32 v61, v61
	v_cvt_i32_f32_e32 v63, v64
	v_cmp_ngt_f32_e32 vcc, s11, v60
	v_ldexp_f32 v61, v61, v63
	s_nop 0
	v_cndmask_b32_e32 v61, 0, v61, vcc
	v_cmp_nlt_f32_e32 vcc, s6, v60
	s_movk_i32 s6, 0x200
	s_nop 0
	v_cndmask_b32_e32 v60, v220, v61, vcc
	v_sub_f32_e32 v59, v59, v60
	ds_bpermute_b32 v60, v176, v58
	v_add_f32_e32 v59, v236, v59
	v_cndmask_b32_e64 v59, -v59, 1.0, s[40:41]
	s_waitcnt lgkmcnt(0)
	v_add_f32_e32 v58, v58, v60
	ds_bpermute_b32 v60, v1, v58
	s_waitcnt lgkmcnt(0)
	v_add_f32_e32 v58, v58, v60
	ds_bpermute_b32 v60, v176, v62
	s_waitcnt lgkmcnt(0)
	v_add_f32_e32 v60, v62, v60
	ds_bpermute_b32 v61, v1, v60
	s_waitcnt lgkmcnt(0)
	v_add_f32_e32 v60, v60, v61
	v_div_scale_f32 v61, s[10:11], v58, v58, v59
	v_rcp_f32_e32 v62, v61
	s_nop 0
	v_fma_f32 v63, -v61, v62, 1.0
	v_fmac_f32_e32 v62, v63, v62
	v_div_scale_f32 v63, vcc, v59, v58, v59
	v_mul_f32_e32 v64, v63, v62
	v_fma_f32 v65, -v61, v64, v63
	v_fmac_f32_e32 v64, v65, v62
	v_fma_f32 v61, -v61, v64, v63
	v_div_fmas_f32 v61, v61, v62, v64
	v_div_fixup_f32 v62, v61, v58, v59
	v_div_scale_f32 v58, s[10:11], v60, v60, v59
	v_rcp_f32_e32 v61, v58
	s_nop 0
	v_fma_f32 v63, -v58, v61, 1.0
	v_fmac_f32_e32 v61, v63, v61
	v_div_scale_f32 v63, vcc, v59, v60, v59
	v_mul_f32_e32 v64, v63, v61
	v_fma_f32 v65, -v58, v64, v63
	v_fmac_f32_e32 v64, v65, v61
	v_fma_f32 v58, -v58, v64, v63
	v_div_fmas_f32 v58, v58, v61, v64
	v_div_fixup_f32 v64, v58, v60, v59
	v_lshlrev_b32_e32 v58, 13, v182
	v_lshlrev_b32_e32 v59, 4, v181
	v_pk_mul_f32 v[66:67], v[90:91], v[64:65] op_sel_hi:[1,0]
	v_pk_mul_f32 v[68:69], v[92:93], v[64:65] op_sel_hi:[1,0]
	v_pk_mul_f32 v[70:71], v[78:79], v[62:63] op_sel_hi:[1,0]
	v_pk_mul_f32 v[72:73], v[80:81], v[62:63] op_sel_hi:[1,0]
	v_pk_mul_f32 v[74:75], v[10:11], v[64:65] op_sel_hi:[1,0]
	v_pk_mul_f32 v[76:77], v[12:13], v[64:65] op_sel_hi:[1,0]
	v_pk_mul_f32 v[78:79], v[2:3], v[62:63] op_sel_hi:[1,0]
	v_pk_mul_f32 v[80:81], v[4:5], v[62:63] op_sel_hi:[1,0]
	v_add3_u32 v84, 0, v58, v59
	v_cndmask_b32_e64 v61, v73, v69, s[40:41]
	v_cndmask_b32_e64 v60, v72, v68, s[40:41]
	v_cndmask_b32_e64 v59, v71, v67, s[40:41]
	v_cndmask_b32_e64 v58, v70, v66, s[40:41]
	v_cndmask_b32_e64 v5, v81, v77, s[40:41]
	v_cndmask_b32_e64 v4, v80, v76, s[40:41]
	v_cndmask_b32_e64 v3, v79, v75, s[40:41]
	v_cndmask_b32_e64 v2, v78, v74, s[40:41]
	v_pk_mul_f32 v[54:55], v[54:55], v[64:65] op_sel_hi:[1,0]
	v_pk_mul_f32 v[56:57], v[56:57], v[64:65] op_sel_hi:[1,0]
	v_pk_mul_f32 v[42:43], v[42:43], v[62:63] op_sel_hi:[1,0]
	v_pk_mul_f32 v[44:45], v[44:45], v[62:63] op_sel_hi:[1,0]
	ds_write_b128 v84, v[58:61]
	v_pk_mul_f32 v[50:51], v[50:51], v[64:65] op_sel_hi:[1,0]
	v_pk_mul_f32 v[52:53], v[52:53], v[64:65] op_sel_hi:[1,0]
	v_pk_mul_f32 v[58:59], v[14:15], v[62:63] op_sel_hi:[1,0]
	v_pk_mul_f32 v[60:61], v[16:17], v[62:63] op_sel_hi:[1,0]
	ds_write_b128 v84, v[2:5] offset:3072
	v_cndmask_b32_e64 v5, v45, v57, s[40:41]
	v_cndmask_b32_e64 v4, v44, v56, s[40:41]
	v_cndmask_b32_e64 v3, v43, v55, s[40:41]
	v_cndmask_b32_e64 v2, v42, v54, s[40:41]
	v_pk_mul_f32 v[46:47], v[46:47], v[64:65] op_sel_hi:[1,0]
	v_pk_mul_f32 v[48:49], v[48:49], v[64:65] op_sel_hi:[1,0]
	v_pk_mul_f32 v[38:39], v[38:39], v[62:63] op_sel_hi:[1,0]
	v_pk_mul_f32 v[82:83], v[40:41], v[62:63] op_sel_hi:[1,0]
	v_cndmask_b32_e64 v17, v61, v53, s[40:41]
	v_cndmask_b32_e64 v16, v60, v52, s[40:41]
	v_cndmask_b32_e64 v15, v59, v51, s[40:41]
	v_cndmask_b32_e64 v14, v58, v50, s[40:41]
	ds_write_b128 v84, v[2:5] offset:4096
	v_cndmask_b32_e64 v5, v83, v49, s[40:41]
	v_cndmask_b32_e64 v4, v82, v48, s[40:41]
	v_cndmask_b32_e64 v3, v39, v47, s[40:41]
	v_cndmask_b32_e64 v2, v38, v46, s[40:41]
	v_pk_mul_f32 v[30:31], v[30:31], v[64:65] op_sel_hi:[1,0]
	v_pk_mul_f32 v[32:33], v[32:33], v[64:65] op_sel_hi:[1,0]
	v_pk_mul_f32 v[26:27], v[26:27], v[62:63] op_sel_hi:[1,0]
	v_pk_mul_f32 v[28:29], v[28:29], v[62:63] op_sel_hi:[1,0]
	ds_write_b128 v84, v[14:17] offset:1024
	v_pk_mul_f32 v[14:15], v[34:35], v[64:65] op_sel_hi:[1,0]
	v_pk_mul_f32 v[16:17], v[36:37], v[64:65] op_sel_hi:[1,0]
	v_pk_mul_f32 v[34:35], v[6:7], v[62:63] op_sel_hi:[1,0]
	v_pk_mul_f32 v[36:37], v[8:9], v[62:63] op_sel_hi:[1,0]
	ds_write_b128 v84, v[2:5] offset:5120
	v_cndmask_b32_e64 v5, v29, v33, s[40:41]
	v_cndmask_b32_e64 v4, v28, v32, s[40:41]
	v_cndmask_b32_e64 v3, v27, v31, s[40:41]
	v_cndmask_b32_e64 v2, v26, v30, s[40:41]
	v_pk_mul_f32 v[22:23], v[22:23], v[64:65] op_sel_hi:[1,0]
	v_pk_mul_f32 v[24:25], v[24:25], v[64:65] op_sel_hi:[1,0]
	v_pk_mul_f32 v[64:65], v[18:19], v[62:63] op_sel_hi:[1,0]
	v_pk_mul_f32 v[62:63], v[20:21], v[62:63] op_sel_hi:[1,0]
	ds_write_b128 v84, v[2:5] offset:6144
	v_cndmask_b32_e64 v5, v63, v25, s[40:41]
	v_cndmask_b32_e64 v4, v62, v24, s[40:41]
	v_cndmask_b32_e64 v3, v65, v23, s[40:41]
	v_cndmask_b32_e64 v2, v64, v22, s[40:41]
	ds_write_b128 v84, v[2:5] offset:7168
	v_lshlrev_b32_e32 v2, 9, v182
	v_cndmask_b32_e64 v9, v37, v17, s[40:41]
	v_cndmask_b32_e64 v8, v36, v16, s[40:41]
	v_cndmask_b32_e64 v7, v35, v15, s[40:41]
	v_cndmask_b32_e64 v6, v34, v14, s[40:41]
	v_bitop3_b32 v2, v2, s6, v181 bitop3:0x36
	ds_write_b128 v84, v[6:9] offset:2048
	v_lshl_add_u32 v84, v2, 4, 0
	s_waitcnt lgkmcnt(0)
	s_barrier
	s_add_u32 s100, s100, s14
	s_addc_u32 s101, s101, s15
	v_lshlrev_b32_e32 v132, 4, v178
	global_load_dwordx4 v[100:103], v132, s[100:101]
	global_load_dwordx4 v[104:107], v132, s[100:101] offset:64
	global_load_dwordx4 v[108:111], v132, s[100:101] offset:128
	global_load_dwordx4 v[112:115], v132, s[100:101] offset:192
	global_load_dwordx4 v[116:119], v132, s[100:101] offset:256
	global_load_dwordx4 v[120:123], v132, s[100:101] offset:320
	global_load_dwordx4 v[124:127], v132, s[100:101] offset:384
	global_load_dwordx4 v[128:131], v132, s[100:101] offset:448
	ds_read_b128 v[2:5], v84
	ds_read_b128 v[6:9], v84 offset:1024
	v_cndmask_b32_e64 v67, v67, v71, s[40:41]
	v_cndmask_b32_e64 v66, v66, v70, s[40:41]
	v_cndmask_b32_e64 v69, v69, v73, s[40:41]
	v_cndmask_b32_e64 v68, v68, v72, s[40:41]
	v_cndmask_b32_e64 v73, v75, v79, s[40:41]
	v_cndmask_b32_e64 v72, v74, v78, s[40:41]
	v_cndmask_b32_e64 v75, v77, v81, s[40:41]
	v_cndmask_b32_e64 v74, v76, v80, s[40:41]
	v_cndmask_b32_e64 v77, v47, v39, s[40:41]
	v_cndmask_b32_e64 v76, v46, v38, s[40:41]
	s_waitcnt lgkmcnt(1)
	v_pk_add_f32 v[38:39], v[66:67], v[2:3]
	v_cndmask_b32_e64 v71, v17, v37, s[40:41]
	v_mul_f32_e32 v66, v39, v39
	v_cndmask_b32_e64 v70, v16, v36, s[40:41]
	v_pk_add_f32 v[36:37], v[68:69], v[4:5]
	v_fmac_f32_e32 v66, v38, v38
	v_cndmask_b32_e64 v59, v51, v59, s[40:41]
	v_cndmask_b32_e64 v58, v50, v58, s[40:41]
	ds_read_b128 v[10:13], v84 offset:2048
	v_fmac_f32_e32 v66, v36, v36
	v_cndmask_b32_e64 v53, v53, v61, s[40:41]
	v_cndmask_b32_e64 v52, v52, v60, s[40:41]
	v_cndmask_b32_e64 v61, v15, v35, s[40:41]
	v_cndmask_b32_e64 v60, v14, v34, s[40:41]
	v_fmac_f32_e32 v66, v37, v37
	s_waitcnt lgkmcnt(1)
	v_pk_add_f32 v[34:35], v[58:59], v[6:7]
	v_cndmask_b32_e64 v79, v49, v83, s[40:41]
	v_fmac_f32_e32 v66, v34, v34
	v_cndmask_b32_e64 v78, v48, v82, s[40:41]
	v_cndmask_b32_e64 v83, v33, v29, s[40:41]
	v_cndmask_b32_e64 v82, v32, v28, s[40:41]
	v_pk_add_f32 v[32:33], v[52:53], v[8:9]
	v_fmac_f32_e32 v66, v35, v35
	ds_read_b128 v[14:17], v84 offset:3072
	v_fmac_f32_e32 v66, v32, v32
	v_cndmask_b32_e64 v81, v31, v27, s[40:41]
	v_cndmask_b32_e64 v80, v30, v26, s[40:41]
	v_fmac_f32_e32 v66, v33, v33
	s_waitcnt lgkmcnt(1)
	v_pk_add_f32 v[30:31], v[60:61], v[10:11]
	v_pk_add_f32 v[28:29], v[70:71], v[12:13]
	v_fmac_f32_e32 v66, v30, v30
	v_fmac_f32_e32 v66, v31, v31
	ds_read_b128 v[18:21], v84 offset:4096
	v_fmac_f32_e32 v66, v28, v28
	v_fmac_f32_e32 v66, v29, v29
	s_waitcnt lgkmcnt(1)
	v_pk_add_f32 v[26:27], v[72:73], v[14:15]
	v_cndmask_b32_e64 v63, v25, v63, s[40:41]
	v_fmac_f32_e32 v66, v26, v26
	v_cndmask_b32_e64 v62, v24, v62, s[40:41]
	v_pk_add_f32 v[24:25], v[74:75], v[16:17]
	v_fmac_f32_e32 v66, v27, v27
	v_cndmask_b32_e64 v55, v55, v43, s[40:41]
	v_cndmask_b32_e64 v54, v54, v42, s[40:41]
	ds_read_b128 v[40:43], v84 offset:5120
	v_fmac_f32_e32 v66, v24, v24
	v_cndmask_b32_e64 v65, v23, v65, s[40:41]
	v_cndmask_b32_e64 v64, v22, v64, s[40:41]
	v_fmac_f32_e32 v66, v25, v25
	s_waitcnt lgkmcnt(1)
	v_pk_add_f32 v[22:23], v[54:55], v[18:19]
	v_cndmask_b32_e64 v57, v57, v45, s[40:41]
	v_cndmask_b32_e64 v56, v56, v44, s[40:41]
	v_fmac_f32_e32 v66, v22, v22
	ds_read_b128 v[44:47], v84 offset:6144
	ds_read_b128 v[48:51], v84 offset:7168
	v_pk_add_f32 v[20:21], v[56:57], v[20:21]
	v_fmac_f32_e32 v66, v23, v23
	v_fmac_f32_e32 v66, v20, v20
	v_fmac_f32_e32 v66, v21, v21
	s_waitcnt lgkmcnt(2)
	v_pk_add_f32 v[18:19], v[76:77], v[40:41]
	v_pk_add_f32 v[16:17], v[78:79], v[42:43]
	v_fmac_f32_e32 v66, v18, v18
	v_fmac_f32_e32 v66, v19, v19
	v_fmac_f32_e32 v66, v16, v16
	s_waitcnt lgkmcnt(1)
	v_pk_add_f32 v[14:15], v[80:81], v[44:45]
	v_fmac_f32_e32 v66, v17, v17
	v_pk_mul_f32 v[4:5], v[14:15], v[14:15]
	v_pk_add_f32 v[12:13], v[82:83], v[46:47]
	v_add_f32_e32 v4, v4, v66
	v_pk_mul_f32 v[2:3], v[12:13], v[12:13]
	v_add_f32_e32 v4, v5, v4
	v_add_f32_e32 v2, v2, v4
	s_waitcnt lgkmcnt(0)
	v_pk_add_f32 v[8:9], v[64:65], v[48:49]
	v_add_f32_e32 v10, v3, v2
	v_pk_mul_f32 v[4:5], v[8:9], v[8:9]
	v_pk_add_f32 v[6:7], v[62:63], v[50:51]
	v_add_f32_e32 v4, v4, v10
	v_pk_mul_f32 v[2:3], v[6:7], v[6:7]
	v_add_f32_e32 v4, v5, v4
	v_add_f32_e32 v2, v2, v4
	v_add_f32_e32 v2, v3, v2
	ds_bpermute_b32 v3, v176, v2
	s_load_dwordx2 s[10:11], s[44:45], 0x80
	v_lshlrev_b32_e32 v4, 3, v178
	v_mov_b32_e32 v5, v0
	s_mov_b32 s6, 0x18a10000
	s_waitcnt lgkmcnt(0)
	v_add_f32_e32 v2, v2, v3
	ds_bpermute_b32 v1, v1, v2
	s_add_u32 s10, s10, s14
	s_addc_u32 s11, s11, s15
	s_mov_b64 s[14:15], 0x18a10000
	v_lshlrev_b32_e32 v44, 4, v178
	s_waitcnt lgkmcnt(0)
	v_add_f32_e32 v1, v2, v1
	v_fmamk_f32 v1, v1, 0x3c000000, v234
	v_cmp_gt_f32_e32 vcc, s90, v1
	v_mul_f32_e32 v2, 0x4b800000, v1
	s_nop 0
	v_cndmask_b32_e32 v1, v1, v2, vcc
	v_rsq_f32_e32 v1, v1
	s_nop 0
	v_mul_f32_e32 v2, 0x45800000, v1
	v_cndmask_b32_e32 v1, v1, v2, vcc
	v_lshlrev_b32_e32 v2, 4, v179
	v_or3_b32 v2, v2, v177, v180
	v_ashrrev_i32_e32 v3, 31, v2
	v_lshlrev_b64 v[2:3], 11, v[2:3]
	v_lshl_add_u64 v[2:3], s[42:43], 0, v[2:3]
	v_lshl_add_u64 v[2:3], v[2:3], 0, s[30:31]
	v_lshl_add_u64 v[2:3], v[2:3], 0, v[4:5]
	v_add_co_u32_e32 v40, vcc, s6, v2
	v_lshl_add_u64 v[10:11], v[2:3], 0, s[14:15]
	s_nop 0
	v_addc_co_u32_e32 v41, vcc, 0, v3, vcc
	v_mul_f32_e32 v1, v227, v1
	v_mul_f32_e32 v38, v38, v1
	v_mul_f32_e32 v36, v36, v1
	v_mul_f32_e32 v34, v34, v1
	v_mul_f32_e32 v32, v32, v1
	v_mul_f32_e32 v30, v30, v1
	v_mul_f32_e32 v28, v28, v1
	v_mul_f32_e32 v26, v26, v1
	v_mul_f32_e32 v24, v24, v1
	v_mul_f32_e32 v22, v22, v1
	v_mul_f32_e32 v20, v20, v1
	v_mul_f32_e32 v18, v18, v1
	v_mul_f32_e32 v16, v16, v1
	v_mul_f32_e32 v14, v14, v1
	v_mul_f32_e32 v12, v12, v1
	s_waitcnt vmcnt(0)
	v_readfirstlane_b32 s101, v224
	v_mov_b32_e32 v42, v146
	v_mov_b32_e32 v43, v147
	v_mov_b32_e32 v2, v100
	v_mov_b32_e32 v3, v101
	v_mov_b32_e32 v4, v102
	v_mov_b32_e32 v5, v103
	v_mul_f32_e32 v2, v2, v38
	v_lshlrev_b32_e32 v38, 16, v42
	v_mul_f32_e32 v2, v2, v38
	v_mul_f32_e32 v38, v39, v1
	v_mul_f32_e32 v4, v4, v36
	v_lshlrev_b32_e32 v36, 16, v43
	v_mul_f32_e32 v3, v3, v38
	v_and_b32_e32 v38, 0xffff0000, v42
	v_mul_f32_e32 v4, v4, v36
	v_mul_f32_e32 v36, v37, v1
	v_mul_f32_e32 v3, v3, v38
	v_mul_f32_e32 v5, v5, v36
	v_and_b32_e32 v36, 0xffff0000, v43
	v_mul_f32_e32 v5, v5, v36
	s_nop 1
	v_cvt_pk_bf16_f32 v2, v2, v3
	s_nop 1
	v_cvt_pk_bf16_f32 v3, v4, v5
	global_store_dwordx2 v[40:41], v[2:3], off
	v_mov_b32_e32 v36, v148
	v_mov_b32_e32 v37, v149
	s_nop 0
	v_mov_b32_e32 v2, v104
	v_mov_b32_e32 v3, v105
	v_mov_b32_e32 v4, v106
	v_mov_b32_e32 v5, v107
	v_mul_f32_e32 v2, v2, v34
	v_lshlrev_b32_e32 v34, 16, v36
	v_mul_f32_e32 v2, v2, v34
	v_mul_f32_e32 v34, v35, v1
	v_mul_f32_e32 v4, v4, v32
	v_lshlrev_b32_e32 v32, 16, v37
	v_mul_f32_e32 v3, v3, v34
	v_and_b32_e32 v34, 0xffff0000, v36
	v_mul_f32_e32 v4, v4, v32
	v_mul_f32_e32 v32, v33, v1
	v_mul_f32_e32 v3, v3, v34
	v_mul_f32_e32 v5, v5, v32
	v_and_b32_e32 v32, 0xffff0000, v37
	v_mul_f32_e32 v5, v5, v32
	s_nop 1
	v_cvt_pk_bf16_f32 v2, v2, v3
	s_nop 1
	v_cvt_pk_bf16_f32 v3, v4, v5
	global_store_dwordx2 v[10:11], v[2:3], off offset:32
	v_mov_b32_e32 v32, v150
	v_mov_b32_e32 v33, v151
	s_nop 0
	v_mov_b32_e32 v2, v108
	v_mov_b32_e32 v3, v109
	v_mov_b32_e32 v4, v110
	v_mov_b32_e32 v5, v111
	v_mul_f32_e32 v2, v2, v30
	v_lshlrev_b32_e32 v30, 16, v32
	v_mul_f32_e32 v2, v2, v30
	v_mul_f32_e32 v30, v31, v1
	v_mul_f32_e32 v4, v4, v28
	v_lshlrev_b32_e32 v28, 16, v33
	v_mul_f32_e32 v3, v3, v30
	v_and_b32_e32 v30, 0xffff0000, v32
	v_mul_f32_e32 v4, v4, v28
	v_mul_f32_e32 v28, v29, v1
	v_mul_f32_e32 v3, v3, v30
	v_mul_f32_e32 v5, v5, v28
	v_and_b32_e32 v28, 0xffff0000, v33
	v_mul_f32_e32 v5, v5, v28
	s_nop 1
	v_cvt_pk_bf16_f32 v2, v2, v3
	s_nop 1
	v_cvt_pk_bf16_f32 v3, v4, v5
	global_store_dwordx2 v[10:11], v[2:3], off offset:64
	v_mov_b32_e32 v28, v152
	v_mov_b32_e32 v29, v153
	s_nop 0
	v_mov_b32_e32 v2, v112
	v_mov_b32_e32 v3, v113
	v_mov_b32_e32 v4, v114
	v_mov_b32_e32 v5, v115
	v_mul_f32_e32 v2, v2, v26
	v_lshlrev_b32_e32 v26, 16, v28
	v_mul_f32_e32 v2, v2, v26
	v_mul_f32_e32 v26, v27, v1
	v_mul_f32_e32 v4, v4, v24
	v_lshlrev_b32_e32 v24, 16, v29
	v_mul_f32_e32 v3, v3, v26
	v_and_b32_e32 v26, 0xffff0000, v28
	v_mul_f32_e32 v4, v4, v24
	v_mul_f32_e32 v24, v25, v1
	v_mul_f32_e32 v3, v3, v26
	v_mul_f32_e32 v5, v5, v24
	v_and_b32_e32 v24, 0xffff0000, v29
	v_mul_f32_e32 v5, v5, v24
	s_nop 1
	v_cvt_pk_bf16_f32 v2, v2, v3
	s_nop 1
	v_cvt_pk_bf16_f32 v3, v4, v5
	global_store_dwordx2 v[10:11], v[2:3], off offset:96
	v_mov_b32_e32 v24, v188
	v_mov_b32_e32 v25, v189
	s_nop 0
	v_mov_b32_e32 v2, v116
	v_mov_b32_e32 v3, v117
	v_mov_b32_e32 v4, v118
	v_mov_b32_e32 v5, v119
	v_mul_f32_e32 v2, v2, v22
	v_lshlrev_b32_e32 v22, 16, v24
	v_mul_f32_e32 v2, v2, v22
	v_mul_f32_e32 v22, v23, v1
	v_mul_f32_e32 v4, v4, v20
	v_lshlrev_b32_e32 v20, 16, v25
	v_mul_f32_e32 v3, v3, v22
	v_and_b32_e32 v22, 0xffff0000, v24
	v_mul_f32_e32 v4, v4, v20
	v_mul_f32_e32 v20, v21, v1
	v_mul_f32_e32 v3, v3, v22
	v_mul_f32_e32 v5, v5, v20
	v_and_b32_e32 v20, 0xffff0000, v25
	v_mul_f32_e32 v5, v5, v20
	s_nop 1
	v_cvt_pk_bf16_f32 v2, v2, v3
	s_nop 1
	v_cvt_pk_bf16_f32 v3, v4, v5
	global_store_dwordx2 v[10:11], v[2:3], off offset:128
	v_mov_b32_e32 v20, v190
	v_mov_b32_e32 v21, v191
	s_nop 0
	v_mov_b32_e32 v2, v120
	v_mov_b32_e32 v3, v121
	v_mov_b32_e32 v4, v122
	v_mov_b32_e32 v5, v123
	v_mul_f32_e32 v2, v2, v18
	v_lshlrev_b32_e32 v18, 16, v20
	v_mul_f32_e32 v2, v2, v18
	v_mul_f32_e32 v18, v19, v1
	v_mul_f32_e32 v4, v4, v16
	v_lshlrev_b32_e32 v16, 16, v21
	v_mul_f32_e32 v3, v3, v18
	v_and_b32_e32 v18, 0xffff0000, v20
	v_mul_f32_e32 v4, v4, v16
	v_mul_f32_e32 v16, v17, v1
	v_mul_f32_e32 v3, v3, v18
	v_mul_f32_e32 v5, v5, v16
	v_and_b32_e32 v16, 0xffff0000, v21
	v_mul_f32_e32 v5, v5, v16
	s_nop 1
	v_cvt_pk_bf16_f32 v2, v2, v3
	s_nop 1
	v_cvt_pk_bf16_f32 v3, v4, v5
	global_store_dwordx2 v[10:11], v[2:3], off offset:160
	v_mov_b32_e32 v16, v192
	v_mov_b32_e32 v17, v193
	s_nop 0
	v_mov_b32_e32 v2, v124
	v_mov_b32_e32 v3, v125
	v_mov_b32_e32 v4, v126
	v_mov_b32_e32 v5, v127
	v_mul_f32_e32 v2, v2, v14
	v_lshlrev_b32_e32 v14, 16, v16
	v_mul_f32_e32 v2, v2, v14
	v_mul_f32_e32 v14, v15, v1
	v_mul_f32_e32 v4, v4, v12
	v_lshlrev_b32_e32 v12, 16, v17
	v_mul_f32_e32 v3, v3, v14
	v_and_b32_e32 v14, 0xffff0000, v16
	v_mul_f32_e32 v4, v4, v12
	v_mul_f32_e32 v12, v13, v1
	v_mul_f32_e32 v3, v3, v14
	v_mul_f32_e32 v5, v5, v12
	v_and_b32_e32 v12, 0xffff0000, v17
	v_mul_f32_e32 v5, v5, v12
	s_nop 1
	v_cvt_pk_bf16_f32 v2, v2, v3
	s_nop 1
	v_cvt_pk_bf16_f32 v3, v4, v5
	global_store_dwordx2 v[10:11], v[2:3], off offset:192
	v_mov_b32_e32 v2, v194
	v_mov_b32_e32 v3, v195
	s_nop 0
	v_mov_b32_e32 v12, v128
	v_mov_b32_e32 v13, v129
	v_mov_b32_e32 v14, v130
	v_mov_b32_e32 v15, v131
	v_mul_f32_e32 v4, v8, v1
	v_lshlrev_b32_e32 v5, 16, v2
	v_mul_f32_e32 v4, v4, v12
	v_mul_f32_e32 v4, v4, v5
	v_mul_f32_e32 v5, v9, v1
	v_mul_f32_e32 v5, v5, v13
	v_and_b32_e32 v2, 0xffff0000, v2
	v_mul_f32_e32 v2, v5, v2
	v_mul_f32_e32 v5, v6, v1
	v_mul_f32_e32 v1, v7, v1
	v_mul_f32_e32 v5, v5, v14
	v_lshlrev_b32_e32 v6, 16, v3
	v_mul_f32_e32 v1, v1, v15
	v_and_b32_e32 v3, 0xffff0000, v3
	v_mul_f32_e32 v5, v5, v6
	v_mul_f32_e32 v1, v1, v3
	s_nop 1
	v_cvt_pk_bf16_f32 v2, v4, v2
	s_nop 1
	v_cvt_pk_bf16_f32 v3, v5, v1
	global_store_dwordx2 v[10:11], v[2:3], off offset:224
	s_barrier
